# MoBA selected-block unit prologue: the 10-step scalar binary search over the chunk prefix table becomes a two-level 64-lane search (2 LDS round trips)
# speedup vs baseline: 1.0016x; 1.0016x over previous
; #define LAS __attribute__((address_space(3)))
; #define BLK_ISSUE(t) do { const int b_ = (t) % 3; dma_tile(ds, j * 256 + 64 * (t), lds, b_, wave); ALIBI_CB(b_, (float)(64 * (t) + lane)); } while (0)
; __device__ __forceinline__ void moba_sel_unit(LAS char* lds, int bh, int j, int chunk, int n, const bf16_t* H, const unsigned* lists, bf16_t* PO, float* PML, int tid) {
;     const int lane = tid & 63, wave = __builtin_amdgcn_readfirstlane(tid >> 6), r = lane & 31, hh = lane >> 5, b = bh >> 3, h = bh & 7;
;     const unsigned* lb = lists + (size_t)bh * LIST_PER_BH + list_off(j);
;     const int base = chunk * 512, eA = base + 32 * wave + r, eB = eA + 256; const bool validA = eA < n, validB = eB < n;
;     const bf16_t* Hb = H + (size_t)b * SEQ * HQ;
;     const bf16_t* Kg = Hb + C_MK + h * 64; const bf16_t* Vg = Hb + C_MV + h * 64;
;     const DmaSrc ds = dma_src(Kg, Vg, wave, lane);
;     unsigned va0, va1; v_read_bases(lane, va0, va1); { const unsigned lb_ = (unsigned)(size_t)lds + AL_V; va0 += lb_; va1 += lb_; }
;     ...
;     BLK_ISSUE(0); BLK_ISSUE(1);
; __global__ void __launch_bounds__(512, 2) hybrid_fwd(Args a_unused) {
;     ...
;               else if (u < 512 + T) { const unsigned idx = (unsigned)(u - 512); int lo = 0, hi = 1024;
;                   while (hi - lo > 1) { const int mid = (lo + hi) >> 1; if (lpre[mid] <= idx) lo = mid; else hi = mid; }
;                   moba_sel_unit((LAS char*)lds, lo >> 6, lo & 63, (int)(idx - lpre[lo]), (int)lcnt[lo], H, (const unsigned*)(ws + WS_LIST), (bf16_t*)(ws + WS_PO), (float*)(ws + WS_PML), tid); }
.LBB0_437:
	s_and_b64 vcc, exec, s[18:19]
	s_cbranch_vccz .LBB0_503
	s_add_i32 s5, s7, 0xfffffe00
	v_mbcnt_lo_u32_b32 v0, -1, 0
	v_mbcnt_hi_u32_b32 v0, -1, v0
	v_lshlrev_b32_e32 v2, 6, v0
	ds_read_b32 v2, v2 offset:54272
	s_waitcnt lgkmcnt(0)
	v_cmp_ge_u32_e32 vcc, s5, v2
	s_bcnt1_i32_b64 s0, vcc
	s_add_i32 s0, s0, -1
	s_lshl_b32 s0, s0, 4
	v_and_b32_e32 v2, 15, v0
	v_add_lshl_u32 v2, v2, s0, 2
	ds_read_b32 v2, v2 offset:54272
	s_waitcnt lgkmcnt(0)
	v_cmp_ge_u32_e32 vcc, s5, v2
	s_and_b32 s1, vcc_lo, 0xffff
	s_bcnt1_i32_b32 s1, s1
	s_add_i32 s0, s0, s1
	s_add_i32 s0, s0, -1
	s_ashr_i32 s12, s0, 6
	s_lshl_b32 s3, s0, 2
	v_readfirstlane_b32 s17, v151
	s_ashr_i32 s28, s0, 9
	s_and_b32 s1, s0, 63
	s_add_i32 s3, s3, 0
	s_ashr_i32 s13, s17, 6
	s_and_b32 s0, s12, 7
	s_mul_i32 s11, s28, 0xa800000
	v_mov_b32_e32 v0, s3
	s_mul_hi_i32 s3, s28, 0xa800000
	s_add_u32 s48, s24, s11
	ds_read2st64_b32 v[2:3], v0 offset0:196 offset1:212
	s_addc_u32 s49, s25, s3
	s_lshl_b32 s3, s0, 7
	s_add_u32 s3, s48, s3
	s_addc_u32 s11, s49, 0
	v_lshl_or_b32 v4, s13, 3, v186
	s_add_u32 s18, s3, 0x1e00
	v_ashrrev_i32_e32 v5, 1, v4
	s_addc_u32 s19, s11, 0
	v_xor_b32_e32 v0, v5, v146
	s_waitcnt lgkmcnt(0)
	v_readfirstlane_b32 s16, v3
	v_readfirstlane_b32 s4, v2
	v_mov_b64_e32 v[2:3], s[18:19]
	v_lshlrev_b32_e32 v0, 4, v0
	s_add_u32 s20, s3, 0x2200
	v_mad_i64_i32 v[2:3], s[18:19], v4, s15, v[2:3]
	v_and_b32_e32 v0, 0x70, v0
	s_addc_u32 s21, s11, 0
	v_lshl_add_u64 v[138:139], v[2:3], 0, v[0:1]
	v_lshlrev_b32_e32 v0, 2, v5
	s_mul_i32 s3, s1, 0x150000
	v_mov_b64_e32 v[2:3], s[20:21]
	v_bitop3_b32 v0, v0, v187, 4 bitop3:0x6c
	s_lshl_b32 s66, s3, 1
	s_lshl_b32 s3, s13, 10
	v_mad_i64_i32 v[2:3], s[18:19], v4, s15, v[2:3]
	v_lshlrev_b32_e32 v0, 4, v0
	s_mov_b32 s67, s31
	s_add_i32 s3, s3, 0
	v_lshl_add_u64 v[140:141], v[2:3], 0, v[0:1]
	v_lshl_add_u64 v[2:3], v[138:139], 0, s[66:67]
	s_mov_b32 m0, s3
	s_add_i32 s11, s3, 0x6000
	global_load_lds_dwordx4 v[2:3], off
	v_lshl_add_u64 v[2:3], v[140:141], 0, s[66:67]
	s_mov_b32 m0, s11
	s_cmp_lt_u32 s17, 64
	global_load_lds_dwordx4 v[2:3], off
	s_cselect_b64 s[18:19], -1, 0
	s_cmp_gt_u32 s17, 63
	s_mov_b64 s[44:45], -1
	s_cbranch_scc0 .LBB0_442
	s_add_i32 s30, s66, 0xa8000
	v_lshl_add_u64 v[2:3], v[138:139], 0, s[30:31]
	s_add_i32 m0, s3, 0x2000
	s_mov_b64 s[44:45], 0
	global_load_lds_dwordx4 v[2:3], off
	v_lshl_add_u64 v[2:3], v[140:141], 0, s[30:31]
	s_add_i32 m0, s3, 0x8000
	s_nop 0
	global_load_lds_dwordx4 v[2:3], off
